# neighbourhood attention: redundant clamped-row LDS-DMA pieces not issued; row waits count exactly the pieces of rows still ahead (vmcnt 8/6/4/2/0)
# speedup vs baseline: 1.0099x; 1.0099x over previous
.LBB0_235:
	s_mul_hi_u32 s11, s8, 0x24924925
	s_sub_i32 s74, s8, s11
	s_lshr_b32 s74, s74, 1
	s_add_i32 s74, s74, s11
	s_lshr_b32 s11, s74, 2
	s_add_i32 s74, s6, s87
	s_add_i32 s76, s74, 8
	s_add_i32 s74, s87, 17
	s_cmp_gt_i32 s74, s95
	s_cselect_b32 s100, 1, 0
	s_min_i32 s74, s74, s95
	v_add_u32_e32 v66, s74, v65
	v_lshlrev_b32_e32 v68, 6, v66
	s_mul_i32 s11, s11, 0x1c000
	v_add_u32_e32 v66, v68, v141
	s_sub_i32 s11, s9, s11
	v_ashrrev_i32_e32 v67, 31, v66
	v_or_b32_e32 v68, v68, v145
	s_sub_i32 s101, s95, s87
	s_addk_i32 s101, 0xfff4
	s_cmp_gt_i32 s101, 3
	s_cbranch_scc1 .Lna_w8
	s_cmp_eq_u32 s101, 3
	s_cbranch_scc1 .Lna_w6
	s_cmp_eq_u32 s101, 2
	s_cbranch_scc1 .Lna_w4
	s_cmp_eq_u32 s101, 1
	s_cbranch_scc1 .Lna_w2
	s_waitcnt vmcnt(0) lgkmcnt(0)
	s_branch .Lna_wj
.Lna_w2:
	s_waitcnt vmcnt(2) lgkmcnt(0)
	s_branch .Lna_wj
.Lna_w4:
	s_waitcnt vmcnt(4) lgkmcnt(0)
	s_branch .Lna_wj
.Lna_w6:
	s_waitcnt vmcnt(6) lgkmcnt(0)
	s_branch .Lna_wj
.Lna_w8:
	s_waitcnt vmcnt(8) lgkmcnt(0)
